# attention: static priority raise for waves 4-7 during attention units
# baseline (speedup 1.0000x reference)
.LBB0_820:
	s_setprio 0
	s_add_i32 s49, s49, s3
	s_cmp_ge_i32 s49, s48
	s_waitcnt lgkmcnt(0)
	s_cbranch_scc1 .LBB0_796
.LBB0_821:
	v_readfirstlane_b32 s100, v0
	s_nop 1
	s_lshr_b32 s100, s100, 6
	s_cmp_lt_u32 s100, 4
	s_cbranch_scc1 .Lmy_att_noprio
	s_setprio 1
